# attention tile loop restructured: MFMA-first heads (PV s0 / QK first half issued under the row-max chain), score copies removed (subs read QK registers), SADDR LDS-DMA; rcp-based f32 division in epilo
# speedup vs baseline: 1.0527x; 1.0089x over previous
.LBB0_78:
	s_add_u32 s69, s82, 0x1f200000
	s_addc_u32 s4, s83, 0
	v_writelane_b32 v252, s4, 45
	s_add_u32 s4, s82, 0x1f280000
	v_writelane_b32 v252, s4, 46
	s_addc_u32 s4, s83, 0
	v_writelane_b32 v252, s4, 47
	s_add_u32 s4, s82, 0x1fa80000
	s_addc_u32 s5, s83, 0
	v_writelane_b32 v252, s4, 48
	s_barrier
	s_nop 0
	v_writelane_b32 v252, s5, 49
	s_nop 0
	v_readlane_b32 s4, v252, 0
	v_readlane_b32 s5, v252, 1
	s_load_dwordx2 s[10:11], s[0:1], 0xd0
	s_add_u32 s34, s82, 0x1f680000
	v_readlane_b32 s4, v252, 0
	s_addc_u32 s35, s83, 0
	v_readlane_b32 s5, v252, 1
	s_nop 1
	s_mov_b32 s84, s4
	s_waitcnt lgkmcnt(0)
	s_mov_b32 s85, 0
	s_mov_b32 s87, 0
	s_movk_i32 s86, 0xdff
	s_movk_i32 s47, 0x7bff
	s_cmp_eq_u32 s10, 0x100
	s_cbranch_scc0 .Ls5p_nosplit
	s_lshr_b32 s85, s4, 6
	s_lshl_b32 s87, s85, 13
	s_lshl_b32 s85, s85, 10
	s_and_b32 s4, s4, 63
	s_add_i32 s86, s85, 0x1ff
	s_add_i32 s47, s87, 0x1bff
.Ls5p_nosplit:
	s_cmp_gt_i32 s4, 63
	s_cbranch_scc1 .LBB0_111
	s_mov_b32 s20, s4
	s_ashr_i32 s21, s4, 31
	s_lshl_b32 s36, s4, 6
	s_lshl_b32 s37, s10, 6
	s_lshl_b32 s38, s4, 10
	s_lshl_b32 s39, s10, 10
	s_lshl_b64 s[4:5], s[20:21], 16
	s_add_u32 s8, s82, s4
	s_addc_u32 s9, s83, s5
	s_add_u32 s12, s8, 0x1f280400
	s_addc_u32 s13, s9, 0
	s_ashr_i32 s5, s10, 31
	s_mov_b32 s4, s10
	s_lshl_b64 s[14:15], s[4:5], 16
	s_mov_b32 s4, s84
	s_add_u32 s16, s8, 0x1f680400
	v_mov_b32_e32 v1, 0
	v_writelane_b32 v252, s4, 0
	s_addc_u32 s17, s9, 0
	s_mov_b32 s40, 0x3fb8aa3b
	s_mov_b32 s41, 0xc2ce8ed0
	s_mov_b32 s42, 0x42b17218
	v_mov_b32_e32 v18, 0x3c0881c4
	v_mov_b32_e32 v19, 0xbab64f3b
	s_add_i32 s43, 0, 0x200
	s_add_i32 s44, 0, 0x2200
	s_add_i32 s45, 0, 0x4200
	s_mov_b64 s[18:19], 0x800
	s_movk_i32 s46, 0x1ff
	s_movk_i32 s67, 0x3c0
	v_mov_b32_e32 v20, 0x7f800000
	v_not_b32_e32 v21, 63
	v_not_b32_e32 v22, 31
	v_mov_b32_e32 v23, 0x7fc00000
	v_mov_b32_e32 v2, 1.0
	v_mov_b32_e32 v3, v1
	v_writelane_b32 v252, s5, 1
	s_branch .LBB0_81

.LBB0_93:
	s_or_b64 exec, exec, s[4:5]
	s_movk_i32 s4, 0x1000
	v_cmp_gt_i32_e32 vcc, s4, v4
	v_and_b32_e32 v0, 15, v4
	s_waitcnt lgkmcnt(0)
	s_barrier
	s_and_saveexec_b64 s[8:9], vcc
	s_cbranch_execz .LBB0_100
	s_ashr_i32 s21, s20, 31
	s_lshl_b32 s24, s20, 4
	s_lshl_b64 s[4:5], s[20:21], 13
	s_add_u32 s10, s69, s4
	v_readlane_b32 s4, v252, 45
	s_addc_u32 s11, s4, s5
	v_lshl_add_u32 v5, v0, 3, s44
	s_mov_b64 s[22:23], 0
	v_add_u32_e32 v6, s85, v4
	s_branch .LBB0_96
.LBB0_95:
	s_or_b64 exec, exec, s[4:5]
	v_ashrrev_i32_e32 v7, 31, v6
	s_mov_b32 s4, s86
	v_cvt_pk_bf16_f32 v10, v8, s0
	v_lshl_add_u64 v[8:9], v[6:7], 1, s[10:11]
	v_add_u32_e32 v7, 0x200, v6
	v_cmp_lt_i32_e32 vcc, s4, v6
	s_or_b64 s[22:23], vcc, s[22:23]
	v_mov_b32_e32 v6, v7
	global_store_short v[8:9], v10, off
	s_andn2_b64 exec, exec, s[22:23]
	s_cbranch_execz .LBB0_100

.LBB0_100:
	s_or_b64 exec, exec, s[8:9]
	s_mov_b32 s4, 0x8000
	v_cmp_gt_i32_e32 vcc, s4, v4
	s_and_saveexec_b64 s[10:11], vcc
	s_cbranch_execz .LBB0_80
	v_max_i32_e32 v5, 0x7e00, v4
	v_sub_u32_e32 v5, v5, v4
	v_add_u32_e32 v7, 0x1ff, v5
	s_ashr_i32 s21, s20, 31
	v_and_b32_e32 v8, 63, v4
	v_and_b32_e32 v5, 0x200, v7
	s_lshl_b64 s[22:23], s[20:21], 16
	v_lshl_add_u32 v12, v8, 3, 0
	v_cmp_eq_u32_e32 vcc, 0, v5
	v_lshlrev_b32_e32 v11, 2, v4
	v_ashrrev_i32_e32 v5, 31, v4
	v_add_u32_e32 v10, 0x200, v4
	v_add_u32_e32 v6, s87, v4
	s_and_saveexec_b64 s[8:9], vcc
	s_cbranch_execz .LBB0_103
	v_ashrrev_i32_e32 v6, 5, v4
	v_lshlrev_b32_e32 v6, 3, v6
	v_and_b32_e32 v6, 0xfffffe00, v6
	v_lshlrev_b32_e32 v8, 3, v8
	v_add3_u32 v6, 0, v6, v8
	v_and_b32_e32 v8, 0x1e00, v11
	v_add_u32_e32 v13, v12, v8
	ds_read_b64 v[8:9], v6 offset:512
	ds_read_b64 v[14:15], v13 offset:16896
	v_readlane_b32 s4, v252, 46
	s_add_u32 s24, s4, s22
	v_readlane_b32 s4, v252, 47
	v_and_b32_e32 v6, 64, v4
	s_waitcnt lgkmcnt(0)
	v_pk_mul_f32 v[16:17], v[8:9], v[14:15]
	v_pk_mul_f32 v[8:9], v[8:9], v[14:15] op_sel:[1,0] op_sel_hi:[0,1]
	s_addc_u32 s25, s4, s23
	v_sub_f32_e32 v13, v16, v17
	v_add_f32_e32 v8, v8, v9
	v_cmp_eq_u32_e64 s[4:5], 0, v6
	s_nop 1
	v_cndmask_b32_e64 v6, -v8, v13, s[4:5]
	v_cvt_pk_bf16_f32 v6, v6, s0
	v_lshl_add_u64 v[8:9], v[4:5], 1, s[24:25]
	global_store_short v[8:9], v6, off
	v_add_u32_e32 v6, 0x200, v4

.LBB0_108:
	s_or_b64 exec, exec, s[8:9]
	s_and_b64 exec, exec, s[4:5]
	s_cbranch_execz .LBB0_80
	v_add_u32_e32 v4, s87, v4
	v_ashrrev_i32_e32 v5, 31, v4
	v_lshlrev_b64 v[6:7], 1, v[4:5]
	v_lshlrev_b32_e32 v5, 2, v4
	s_mov_b64 s[8:9], 0
	s_mov_b64 s[22:23], s[16:17]

.LBB0_832:
	s_andn2_b64 vcc, exec, s[0:1]
	s_cbranch_vccnz .LBB0_834
	s_add_i32 s0, s74, s38
	s_addk_i32 s0, 0xc0
	s_mul_i32 s0, s0, s14
	s_lshl_b32 s92, s46, 1
	s_add_i32 s0, s0, s92
	s_addk_i32 s0, 0x1c00
	s_add_u32 s98, s82, s0
	s_addc_u32 s99, s83, 0
	s_lshl_b32 s1, s17, 13
	s_add_u32 s76, s40, s1
	s_addc_u32 s77, s41, 0
	s_add_i32 s0, s78, 0x8000
	s_and_b32 s0, s0, 0x18000
	s_add_i32 s0, s5, s0
	s_mov_b32 m0, s0
	s_nop 0
	global_load_lds_dwordx4 v244, s[98:99]
	s_add_i32 m0, s0, 0x2000
	s_add_u32 s98, s98, 0x80
	s_addc_u32 s99, s99, 0
	global_load_lds_dwordx4 v244, s[98:99]
	s_add_i32 m0, s0, 0x4000
	s_nop 0
	global_load_lds_dwordx4 v245, s[76:77]
	s_add_i32 m0, s0, 0x6000
	s_add_u32 s76, s76, 0x80000
	s_addc_u32 s77, s77, 0
	global_load_lds_dwordx4 v245, s[76:77]
	s_add_i32 s9, s78, 0x10000
	s_and_b32 s33, s9, 0x18000
	s_and_b32 s76, s78, 0x18000
	v_add_u32_e32 v250, s33, v237
	v_add_u32_e32 v250, v250, v228
	ds_read_b128 v[128:131], v250 offset:16384
	ds_read_b128 v[132:135], v250 offset:20480
	ds_read_b128 v[136:139], v250 offset:24576
	ds_read_b128 v[140:143], v250 offset:28672
	v_add_u32_e32 v251, s76, v235
	v_add_u32_e32 v250, v251, v228
	ds_read_b128 v[144:147], v250
	ds_read_b128 v[148:151], v250 offset:4096
	v_add_u32_e32 v250, v251, v231
	ds_read_b128 v[152:155], v250
	ds_read_b128 v[156:159], v250 offset:4096
	v_max3_f32 v246, v64, v65, v66
	v_max3_f32 v247, v72, v73, v74
	v_max3_f32 v248, v80, v81, v82
	v_max3_f32 v249, v88, v89, v90
	v_max3_f32 v246, v246, v67, v68
	v_max3_f32 v247, v247, v75, v76
	v_max3_f32 v248, v248, v83, v84
	v_max3_f32 v249, v249, v91, v92
	s_waitcnt lgkmcnt(7)
	v_mfma_f32_32x32x16_bf16 v[0:15], v[128:131], v[96:99], v[0:15]
	v_max3_f32 v246, v246, v69, v70
	v_max3_f32 v247, v247, v77, v78
	v_max3_f32 v248, v248, v85, v86
	v_max3_f32 v249, v249, v93, v94
	v_max3_f32 v246, v246, v71, v247
	v_max3_f32 v247, v248, v87, v249
	v_max_f32_e32 v248, v212, v212
	s_waitcnt lgkmcnt(6)
	v_mfma_f32_32x32x16_bf16 v[48:63], v[132:135], v[96:99], v[48:63]
	v_max3_f32 v246, v246, v79, v95
	s_nop 0
	v_max3_f32 v246, v246, v247, v247
	s_nop 0
	v_mov_b32_e32 v247, v246
	s_nop 1
	v_permlane32_swap_b32_e32 v246, v247
	v_max3_f32 v246, v246, v247, v247
	s_nop 0
	v_max_f32_e32 v247, v246, v246
	v_max_f32_e32 v251, v248, v247
	s_waitcnt lgkmcnt(5)
	v_mfma_f32_32x32x16_bf16 v[32:47], v[136:139], v[96:99], v[32:47]
	v_sub_f32_e32 v247, v212, v251
	v_exp_f32_e32 v250, v247
	v_add_f32_e32 v247, 0x41000000, v212
	v_cmp_gt_f32_e32 vcc, v246, v247
	s_cmp_eq_u64 vcc, 0
	v_mul_f32_e32 v246, v100, v250
	s_cselect_b64 s[0:1], -1, 0
	v_cndmask_b32_e64 v194, v246, v100, s[0:1]
	s_waitcnt lgkmcnt(4)
	v_mfma_f32_32x32x16_bf16 v[16:31], v[140:143], v[96:99], v[16:31]
	v_cndmask_b32_e64 v212, v251, v212, s[0:1]
	v_mov_b32_e32 v213, v212
	v_sub_f32_e32 v140, v92, v212
	v_sub_f32_e32 v141, v93, v213
	v_sub_f32_e32 v138, v90, v212
	v_sub_f32_e32 v139, v91, v213
	s_waitcnt lgkmcnt(3)
	v_mfma_f32_32x32x16_bf16 v[96:111], v[144:147], v[160:163], 0
	v_sub_f32_e32 v142, v94, v212
	v_sub_f32_e32 v143, v95, v213
	v_sub_f32_e32 v92, v80, v212
	v_sub_f32_e32 v93, v81, v213
	v_sub_f32_e32 v128, v82, v212
	v_sub_f32_e32 v129, v83, v213
	s_waitcnt lgkmcnt(2)
	v_mfma_f32_32x32x16_bf16 v[112:127], v[148:151], v[160:163], 0
	v_sub_f32_e32 v130, v68, v212
	v_sub_f32_e32 v131, v69, v213
	v_sub_f32_e32 v90, v64, v212
	v_sub_f32_e32 v91, v65, v213
	v_sub_f32_e32 v132, v84, v212
	v_sub_f32_e32 v133, v85, v213
	s_waitcnt lgkmcnt(1)
	v_mfma_f32_32x32x16_bf16 v[96:111], v[152:155], v[164:167], v[96:111]
	v_sub_f32_e32 v94, v66, v212
	v_sub_f32_e32 v95, v67, v213
	v_sub_f32_e32 v134, v86, v212
	v_sub_f32_e32 v135, v87, v213
	v_sub_f32_e32 v136, v88, v212
	v_sub_f32_e32 v137, v89, v213
	s_waitcnt lgkmcnt(0)
	v_mfma_f32_32x32x16_bf16 v[112:127], v[156:159], v[164:167], v[112:127]
	v_sub_f32_e32 v144, v70, v212
	v_sub_f32_e32 v145, v71, v213
	v_sub_f32_e32 v148, v74, v212
	v_sub_f32_e32 v149, v75, v213
	v_sub_f32_e32 v150, v76, v212
	v_sub_f32_e32 v151, v77, v213
	v_sub_f32_e32 v146, v72, v212
	v_sub_f32_e32 v147, v73, v213
	v_sub_f32_e32 v152, v78, v212
	v_sub_f32_e32 v153, v79, v213
	v_mov_b32_e32 v68, v250
	s_branch .Lattn_body_1
.LBB0_834:
	v_max3_f32 v64, v144, v145, v146
	v_max3_f32 v65, v152, v153, v154
	v_max3_f32 v66, v128, v129, v130
	v_max3_f32 v67, v136, v137, v138
	s_add_i32 s9, s78, 0x10000
	v_max3_f32 v64, v64, v147, v148
	v_max3_f32 v65, v65, v155, v156
	v_max3_f32 v66, v66, v131, v132
	v_max3_f32 v67, v67, v139, v140
	s_and_b32 s33, s9, 0x18000
	v_max3_f32 v64, v64, v149, v150
	v_max3_f32 v65, v65, v157, v158
	v_max3_f32 v66, v66, v133, v134
	v_max3_f32 v67, v67, v141, v142
	s_and_b32 s76, s78, 0x18000
	v_max3_f32 v64, v64, v151, v65
	v_max3_f32 v65, v66, v135, v67
	v_max_f32_e32 v66, v212, v212
	v_max3_f32 v64, v64, v159, v143
	s_nop 0
	v_max3_f32 v64, v64, v65, v65
	s_nop 0
	v_mov_b32_e32 v65, v64
	s_nop 1
	v_permlane32_swap_b32_e32 v64, v65
	v_max3_f32 v64, v64, v65, v65
	s_nop 0
	v_max_f32_e32 v65, v64, v64
	v_max_f32_e32 v69, v66, v65
	v_sub_f32_e32 v65, v212, v69
	v_exp_f32_e32 v68, v65
	v_add_f32_e32 v65, 0x41000000, v212
	v_cmp_gt_f32_e32 vcc, v64, v65
	s_cmp_eq_u64 vcc, 0
	v_mul_f32_e32 v64, v100, v68
	s_cselect_b64 s[0:1], -1, 0
	v_cndmask_b32_e64 v194, v64, v100, s[0:1]
	v_cndmask_b32_e64 v212, v69, v212, s[0:1]
	v_mov_b32_e32 v213, v212
	v_sub_f32_e32 v92, v128, v212
	v_sub_f32_e32 v93, v129, v213
	v_sub_f32_e32 v128, v130, v212
	v_sub_f32_e32 v129, v131, v213
	v_sub_f32_e32 v130, v148, v212
	v_sub_f32_e32 v131, v149, v213
	v_sub_f32_e32 v90, v144, v212
	v_sub_f32_e32 v91, v145, v213
	v_sub_f32_e32 v132, v132, v212
	v_sub_f32_e32 v133, v133, v213
	v_sub_f32_e32 v144, v150, v212
	v_sub_f32_e32 v145, v151, v213
	v_sub_f32_e32 v148, v154, v212
	v_sub_f32_e32 v149, v155, v213
	v_sub_f32_e32 v150, v156, v212
	v_sub_f32_e32 v151, v157, v213
	v_sub_f32_e32 v140, v140, v212
	v_sub_f32_e32 v141, v141, v213
	v_sub_f32_e32 v138, v138, v212
	v_sub_f32_e32 v139, v139, v213
	v_sub_f32_e32 v94, v146, v212
	v_sub_f32_e32 v95, v147, v213
	v_sub_f32_e32 v146, v152, v212
	v_sub_f32_e32 v147, v153, v213
	v_sub_f32_e32 v152, v158, v212
	v_sub_f32_e32 v153, v159, v213
	v_sub_f32_e32 v142, v142, v212
	v_sub_f32_e32 v143, v143, v213
	v_sub_f32_e32 v134, v134, v212
	v_sub_f32_e32 v135, v135, v213
	v_sub_f32_e32 v136, v136, v212
	v_sub_f32_e32 v137, v137, v213
	v_add_u32_e32 v74, s33, v237
	v_add_u32_e32 v74, v74, v228
	ds_read_b128 v[64:67], v74 offset:16384
	ds_read_b128 v[70:73], v74 offset:20480
	s_waitcnt lgkmcnt(0)
	v_mfma_f32_32x32x16_bf16 v[0:15], v[64:67], v[96:99], v[0:15]
	v_mfma_f32_32x32x16_bf16 v[48:63], v[70:73], v[96:99], v[48:63]
	ds_read_b128 v[64:67], v74 offset:24576
	ds_read_b128 v[70:73], v74 offset:28672
	s_waitcnt lgkmcnt(0)
	v_mfma_f32_32x32x16_bf16 v[32:47], v[64:67], v[96:99], v[32:47]
	v_mfma_f32_32x32x16_bf16 v[16:31], v[70:73], v[96:99], v[16:31]
	v_add_u32_e32 v74, s76, v235
	v_add_u32_e32 v74, v74, v228
	ds_read_b128 v[64:67], v74
	ds_read_b128 v[70:73], v74 offset:4096
	v_add_u32_e32 v74, s76, v235
	v_add_u32_e32 v74, v74, v231
	s_waitcnt lgkmcnt(0)
	v_mfma_f32_32x32x16_bf16 v[96:111], v[64:67], v[160:163], 0
	ds_read_b128 v[64:67], v74
	ds_read_b128 v[74:77], v74 offset:4096
	v_mfma_f32_32x32x16_bf16 v[112:127], v[70:73], v[160:163], 0
	s_waitcnt lgkmcnt(0)
	v_mfma_f32_32x32x16_bf16 v[96:111], v[64:67], v[164:167], v[96:111]
	v_mfma_f32_32x32x16_bf16 v[112:127], v[74:77], v[164:167], v[112:127]
.Lattn_body_1:
	v_add_u32_e32 v239, s33, v237
	v_add_u32_e32 v86, s76, v235
	v_add_u32_e32 v78, v239, v231
	v_add_u32_e32 v82, v86, v230
	v_add_u32_e32 v69, v239, v230
	v_exp_f32_e32 v130, v130
	v_exp_f32_e32 v154, v132
	v_exp_f32_e32 v131, v131
	v_exp_f32_e32 v155, v133
	v_add_u32_e32 v86, v86, v229
	v_exp_f32_e32 v158, v138
	v_exp_f32_e32 v159, v139
	v_exp_f32_e32 v94, v94
	v_exp_f32_e32 v128, v128
	v_exp_f32_e32 v95, v95
	v_exp_f32_e32 v129, v129
	v_exp_f32_e32 v132, v144
	v_exp_f32_e32 v144, v134
	v_exp_f32_e32 v133, v145
	v_exp_f32_e32 v145, v135
	v_exp_f32_e32 v148, v148
	v_exp_f32_e32 v149, v149
	v_exp_f32_e32 v142, v142
	v_exp_f32_e32 v143, v143
	ds_read_b128 v[64:67], v78 offset:16384
	ds_read_b128 v[70:73], v78 offset:20480
	v_exp_f32_e32 v90, v90
	v_exp_f32_e32 v92, v92
	v_exp_f32_e32 v91, v91
	v_exp_f32_e32 v93, v93
	v_exp_f32_e32 v146, v146
	v_exp_f32_e32 v156, v136
	v_exp_f32_e32 v147, v147
	v_exp_f32_e32 v157, v137
	v_add_f32_e32 v136, v90, v92
	v_add_f32_e32 v137, v91, v93
	s_waitcnt lgkmcnt(0)
	v_mfma_f32_32x32x16_bf16 v[0:15], v[64:67], v[184:187], v[0:15]
	ds_read_b128 v[64:67], v78 offset:24576
	ds_read_b128 v[74:77], v78 offset:28672
	ds_read_b128 v[78:81], v82
	ds_read_b128 v[82:85], v82 offset:4096
	v_mfma_f32_32x32x16_bf16 v[48:63], v[70:73], v[184:187], v[48:63]
	ds_read_b128 v[70:73], v86
	ds_read_b128 v[86:89], v86 offset:4096
	s_waitcnt lgkmcnt(0)
	v_mfma_f32_32x32x16_bf16 v[32:47], v[64:67], v[184:187], v[32:47]
	ds_read_b128 v[64:67], v69 offset:16384
	v_mfma_f32_32x32x16_bf16 v[16:31], v[74:77], v[184:187], v[16:31]
	ds_read_b128 v[74:77], v69 offset:20480
	s_waitcnt lgkmcnt(0)
	v_mfma_f32_32x32x16_bf16 v[0:15], v[64:67], v[180:183], v[0:15]
	ds_read_b128 v[64:67], v69 offset:24576
	v_mfma_f32_32x32x16_bf16 v[96:111], v[78:81], v[168:171], v[96:111]
	v_exp_f32_e32 v78, v150
	v_exp_f32_e32 v80, v140
	v_exp_f32_e32 v79, v151
	v_exp_f32_e32 v81, v141
	v_exp_f32_e32 v150, v152
	v_exp_f32_e32 v151, v153
	v_mfma_f32_32x32x16_bf16 v[48:63], v[74:77], v[180:183], v[48:63]
	ds_read_b128 v[74:77], v69 offset:28672
	v_add_u32_e32 v69, v239, v229
	v_add_f32_e64 v134, v150, v142
	v_add_f32_e64 v135, v151, v143
	s_waitcnt lgkmcnt(0)
	v_mfma_f32_32x32x16_bf16 v[32:47], v[64:67], v[180:183], v[32:47]
	ds_read_b128 v[64:67], v69 offset:16384
	v_mfma_f32_32x32x16_bf16 v[96:111], v[70:73], v[172:175], v[96:111]
	v_add_f32_e64 v70, v78, v80
	v_add_f32_e64 v71, v79, v81
	v_add_f32_e64 v72, v130, v154
	v_add_f32_e64 v73, v131, v155
	v_add_f32_e64 v138, v72, v70
	v_add_f32_e64 v139, v73, v71
	ds_read_b128 v[70:73], v69 offset:20480
	v_mfma_f32_32x32x16_bf16 v[16:31], v[74:77], v[180:183], v[16:31]
	v_add_f32_e64 v74, v148, v158
	v_add_f32_e64 v75, v149, v159
	v_add_f32_e64 v76, v94, v128
	v_add_f32_e64 v77, v95, v129
	v_add_f32_e64 v74, v76, v74
	v_add_f32_e64 v75, v77, v75
	v_mfma_f32_32x32x16_bf16 v[112:127], v[82:85], v[168:171], v[112:127]
	v_add_f32_e64 v82, v132, v144
	v_add_f32_e64 v83, v133, v145
	v_add_f32_e64 v84, v146, v156
	v_add_f32_e64 v85, v147, v157
	s_waitcnt lgkmcnt(0)
	v_mfma_f32_32x32x16_bf16 v[0:15], v[64:67], v[176:179], v[0:15]
	v_add_f32_e64 v66, v82, v134
	v_add_f32_e64 v67, v83, v135
	v_add_f32_e64 v64, v136, v84
	v_add_f32_e64 v65, v137, v85
	v_add_f32_e64 v66, v74, v66
	v_add_f32_e64 v67, v75, v67
	ds_read_b128 v[74:77], v69 offset:24576
	v_add_f32_e32 v64, v64, v138
	v_add_f32_e32 v65, v65, v139
	v_cvt_pk_bf16_f32 v134, v154, v155
	v_add_f32_e32 v64, v64, v65
	v_mfma_f32_32x32x16_bf16 v[48:63], v[70:73], v[176:179], v[48:63]
	ds_read_b128 v[70:73], v69 offset:28672
	v_add_f32_e32 v65, v66, v67
	v_add_f32_e32 v82, v64, v65
	v_cvt_pk_bf16_f32 v64, v90, v91
	v_cvt_pk_bf16_f32 v65, v94, v95
	v_cvt_pk_bf16_f32 v66, v130, v131
	v_cvt_pk_bf16_f32 v67, v132, v133
	s_waitcnt lgkmcnt(0)
	v_mfma_f32_32x32x16_bf16 v[32:47], v[74:77], v[176:179], v[32:47]
	v_cvt_pk_bf16_f32 v132, v92, v93
	v_cvt_pk_bf16_f32 v133, v128, v129
	v_cvt_pk_bf16_f32 v135, v144, v145
	v_cvt_pk_bf16_f32 v136, v146, v147
	v_cvt_pk_bf16_f32 v137, v148, v149
	v_cvt_pk_bf16_f32 v138, v78, v79
	v_cvt_pk_bf16_f32 v139, v150, v151
	v_mfma_f32_32x32x16_bf16 v[16:31], v[70:73], v[176:179], v[16:31]
	v_cvt_pk_bf16_f32 v128, v156, v157
	v_cvt_pk_bf16_f32 v129, v158, v159
	v_cvt_pk_bf16_f32 v130, v80, v81
	v_cvt_pk_bf16_f32 v131, v142, v143
	v_add_f32_e32 v69, v194, v82
	v_mfma_f32_32x32x16_bf16 v[112:127], v[86:89], v[172:175], v[112:127]
	s_cbranch_vccz .LBB0_836
	v_pk_mul_f32 v[14:15], v[68:69], v[14:15] op_sel_hi:[0,1]
	v_pk_mul_f32 v[12:13], v[68:69], v[12:13] op_sel_hi:[0,1]
	v_pk_mul_f32 v[10:11], v[68:69], v[10:11] op_sel_hi:[0,1]
	v_pk_mul_f32 v[8:9], v[68:69], v[8:9] op_sel_hi:[0,1]
	v_pk_mul_f32 v[6:7], v[68:69], v[6:7] op_sel_hi:[0,1]
	v_pk_mul_f32 v[4:5], v[68:69], v[4:5] op_sel_hi:[0,1]
	v_pk_mul_f32 v[2:3], v[68:69], v[2:3] op_sel_hi:[0,1]
	v_pk_mul_f32 v[0:1], v[68:69], v[0:1] op_sel_hi:[0,1]
	v_pk_mul_f32 v[62:63], v[68:69], v[62:63] op_sel_hi:[0,1]
	v_pk_mul_f32 v[60:61], v[68:69], v[60:61] op_sel_hi:[0,1]
	v_pk_mul_f32 v[58:59], v[68:69], v[58:59] op_sel_hi:[0,1]
	v_pk_mul_f32 v[56:57], v[68:69], v[56:57] op_sel_hi:[0,1]
	v_pk_mul_f32 v[54:55], v[68:69], v[54:55] op_sel_hi:[0,1]
	v_pk_mul_f32 v[52:53], v[68:69], v[52:53] op_sel_hi:[0,1]
	v_pk_mul_f32 v[50:51], v[68:69], v[50:51] op_sel_hi:[0,1]
	v_pk_mul_f32 v[48:49], v[68:69], v[48:49] op_sel_hi:[0,1]
	v_pk_mul_f32 v[46:47], v[68:69], v[46:47] op_sel_hi:[0,1]
	v_pk_mul_f32 v[44:45], v[68:69], v[44:45] op_sel_hi:[0,1]
	v_pk_mul_f32 v[42:43], v[68:69], v[42:43] op_sel_hi:[0,1]
	v_pk_mul_f32 v[40:41], v[68:69], v[40:41] op_sel_hi:[0,1]
	v_pk_mul_f32 v[38:39], v[68:69], v[38:39] op_sel_hi:[0,1]
	v_pk_mul_f32 v[36:37], v[68:69], v[36:37] op_sel_hi:[0,1]
	v_pk_mul_f32 v[34:35], v[68:69], v[34:35] op_sel_hi:[0,1]
	v_pk_mul_f32 v[32:33], v[68:69], v[32:33] op_sel_hi:[0,1]
	v_pk_mul_f32 v[30:31], v[68:69], v[30:31] op_sel_hi:[0,1]
	v_pk_mul_f32 v[28:29], v[68:69], v[28:29] op_sel_hi:[0,1]
	v_pk_mul_f32 v[26:27], v[68:69], v[26:27] op_sel_hi:[0,1]
	v_pk_mul_f32 v[24:25], v[68:69], v[24:25] op_sel_hi:[0,1]
	v_pk_mul_f32 v[22:23], v[68:69], v[22:23] op_sel_hi:[0,1]
	v_pk_mul_f32 v[20:21], v[68:69], v[20:21] op_sel_hi:[0,1]
	v_pk_mul_f32 v[18:19], v[68:69], v[18:19] op_sel_hi:[0,1]
	v_pk_mul_f32 v[16:17], v[68:69], v[16:17] op_sel_hi:[0,1]

.LBB0_840:
	s_add_i32 s0, s78, 0xffff8000
	s_and_b32 s10, s0, 0x18000
	v_add_u32_e32 v76, s10, v237
	v_add_u32_e32 v76, v76, v228
	ds_read_b128 v[80:83], v76 offset:16384
	ds_read_b128 v[84:87], v76 offset:20480
	ds_read_b128 v[88:91], v76 offset:24576
	ds_read_b128 v[92:95], v76 offset:28672
	v_max3_f32 v68, v96, v97, v98
	v_max3_f32 v70, v104, v105, v106
	v_max3_f32 v71, v112, v113, v114
	v_max3_f32 v72, v120, v121, v122
	v_max3_f32 v68, v68, v99, v100
	v_max3_f32 v70, v70, v107, v108
	v_max3_f32 v71, v71, v115, v116
	v_max3_f32 v72, v72, v123, v124
	s_waitcnt lgkmcnt(3)
	v_mfma_f32_32x32x16_bf16 v[0:15], v[80:83], v[64:67], v[0:15]
	v_max3_f32 v68, v68, v101, v102
	v_max3_f32 v70, v70, v109, v110
	v_max3_f32 v71, v71, v117, v118
	v_max3_f32 v72, v72, v125, v126
	s_xor_b32 s33, s10, 0x10000
	v_max3_f32 v68, v68, v103, v70
	v_max3_f32 v70, v71, v119, v72
	v_max_f32_e32 v71, v212, v212
	s_waitcnt lgkmcnt(2)
	v_mfma_f32_32x32x16_bf16 v[48:63], v[84:87], v[64:67], v[48:63]
	v_max3_f32 v68, v68, v111, v127
	s_nop 0
	v_max3_f32 v68, v68, v70, v70
	s_nop 0
	v_mov_b32_e32 v70, v68
	s_nop 1
	v_permlane32_swap_b32_e32 v68, v70
	v_max3_f32 v68, v68, v70, v70
	s_nop 0
	v_max_f32_e32 v70, v68, v68
	v_max_f32_e32 v141, v71, v70
	s_waitcnt lgkmcnt(1)
	v_mfma_f32_32x32x16_bf16 v[32:47], v[88:91], v[64:67], v[32:47]
	v_sub_f32_e32 v70, v212, v141
	v_exp_f32_e32 v140, v70
	v_add_f32_e32 v70, 0x41000000, v212
	v_cmp_gt_f32_e32 vcc, v68, v70
	s_cmp_eq_u64 vcc, 0
	v_mul_f32_e32 v68, v69, v140
	s_cselect_b64 s[0:1], -1, 0
	v_cndmask_b32_e64 v194, v68, v69, s[0:1]
	s_waitcnt lgkmcnt(0)
	v_mfma_f32_32x32x16_bf16 v[16:31], v[92:95], v[64:67], v[16:31]
	v_add_u32_e32 v182, s10, v237
	v_add_u32_e32 v158, s33, v235
	v_add_u32_e32 v88, v158, v231
	v_add_u32_e32 v150, v182, v231
	v_add_u32_e32 v159, v158, v230
	v_cndmask_b32_e64 v212, v141, v212, s[0:1]
	v_add_u32_e32 v141, v182, v230
	v_mov_b32_e32 v213, v212
	v_sub_f32_e32 v180, v102, v212
	v_sub_f32_e32 v181, v103, v213
	v_sub_f32_e32 v116, v116, v212
	v_sub_f32_e32 v117, v117, v213
	v_sub_f32_e32 v108, v108, v212
	v_sub_f32_e32 v109, v109, v213
	v_sub_f32_e32 v124, v124, v212
	v_sub_f32_e32 v125, v125, v213
	v_exp_f32_e32 v116, v116
	v_exp_f32_e32 v117, v117
	v_exp_f32_e32 v108, v108
	v_exp_f32_e32 v124, v124
	v_exp_f32_e32 v109, v109
	v_add_u32_e32 v68, v158, v228
	v_add_u32_e32 v158, v158, v229
	v_exp_f32_e32 v125, v125
	v_sub_f32_e32 v114, v114, v212
	v_sub_f32_e32 v115, v115, v213
	v_sub_f32_e32 v118, v118, v212
	v_sub_f32_e32 v119, v119, v213
	v_sub_f32_e32 v122, v122, v212
	v_sub_f32_e32 v123, v123, v213
	v_sub_f32_e32 v110, v110, v212
	v_sub_f32_e32 v111, v111, v213
	ds_read_b128 v[64:67], v68
	ds_read_b128 v[80:83], v68 offset:4096
	ds_read_b128 v[84:87], v88
	ds_read_b128 v[142:145], v88 offset:4096
	v_sub_f32_e32 v126, v126, v212
	v_sub_f32_e32 v127, v127, v213
	v_sub_f32_e32 v106, v106, v212
	v_sub_f32_e32 v107, v107, v213
	v_exp_f32_e32 v114, v114
	v_exp_f32_e32 v115, v115
	v_exp_f32_e32 v118, v118
	s_waitcnt lgkmcnt(0)
	v_mfma_f32_32x32x16_bf16 v[64:79], v[64:67], v[160:163], 0
	v_exp_f32_e32 v119, v119
	v_exp_f32_e32 v122, v122
	v_exp_f32_e32 v123, v123
	v_exp_f32_e32 v110, v110
	v_exp_f32_e32 v126, v126
	v_exp_f32_e32 v111, v111
	v_exp_f32_e32 v127, v127
	v_mfma_f32_32x32x16_bf16 v[64:79], v[84:87], v[164:167], v[64:79]
	v_sub_f32_e32 v104, v104, v212
	v_sub_f32_e32 v105, v105, v213
	v_sub_f32_e32 v112, v112, v212
	v_sub_f32_e32 v113, v113, v213
	v_sub_f32_e32 v120, v120, v212
	v_sub_f32_e32 v121, v121, v213
	v_cvt_pk_bf16_f32 v183, v118, v119
	v_exp_f32_e32 v112, v112
	v_exp_f32_e32 v113, v113
	v_exp_f32_e32 v120, v120
	v_mfma_f32_32x32x16_bf16 v[80:95], v[80:83], v[160:163], 0
	v_exp_f32_e32 v121, v121
	v_cvt_pk_bf16_f32 v186, v108, v109
	v_cvt_pk_bf16_f32 v187, v110, v111
	v_mfma_f32_32x32x16_bf16 v[80:95], v[142:145], v[164:167], v[80:95]
	ds_read_b128 v[142:145], v150 offset:16384
	ds_read_b128 v[146:149], v150 offset:20480
	s_waitcnt lgkmcnt(0)
	v_mfma_f32_32x32x16_bf16 v[0:15], v[142:145], v[136:139], v[0:15]
	ds_read_b128 v[142:145], v150 offset:24576
	ds_read_b128 v[150:153], v150 offset:28672
	ds_read_b128 v[154:157], v159
	ds_read_b128 v[176:179], v159 offset:4096
	v_mfma_f32_32x32x16_bf16 v[48:63], v[146:149], v[136:139], v[48:63]
	ds_read_b128 v[146:149], v158
	ds_read_b128 v[238:241], v158 offset:4096
	v_sub_f32_e32 v158, v96, v212
	v_sub_f32_e32 v159, v97, v213
	s_waitcnt lgkmcnt(0)
	v_mfma_f32_32x32x16_bf16 v[32:47], v[142:145], v[136:139], v[32:47]
	v_sub_f32_e32 v142, v98, v212
	v_sub_f32_e32 v143, v99, v213
	v_sub_f32_e32 v144, v100, v212
	v_sub_f32_e32 v145, v101, v213
	ds_read_b128 v[96:99], v141 offset:16384
	ds_read_b128 v[100:103], v141 offset:20480
	s_waitcnt lgkmcnt(0)
	v_mfma_f32_32x32x16_bf16 v[0:15], v[96:99], v[132:135], v[0:15]
	ds_read_b128 v[96:99], v141 offset:24576
	v_mfma_f32_32x32x16_bf16 v[48:63], v[100:103], v[132:135], v[48:63]
	ds_read_b128 v[100:103], v141 offset:28672
	v_add_u32_e32 v141, v182, v229
	v_cvt_pk_bf16_f32 v182, v116, v117
	v_mfma_f32_32x32x16_bf16 v[16:31], v[150:153], v[136:139], v[16:31]
	v_exp_f32_e32 v138, v142
	v_exp_f32_e32 v139, v143
	v_exp_f32_e32 v142, v144
	v_exp_f32_e32 v143, v145
	v_exp_f32_e32 v144, v180
	v_exp_f32_e32 v145, v181
	v_exp_f32_e32 v136, v158
	s_waitcnt lgkmcnt(0)
	v_mfma_f32_32x32x16_bf16 v[32:47], v[96:99], v[132:135], v[32:47]
	ds_read_b128 v[96:99], v141 offset:16384
	v_exp_f32_e32 v137, v159
	v_cvt_pk_bf16_f32 v180, v112, v113
	v_cvt_pk_bf16_f32 v181, v114, v115
	v_add_f32_e32 v152, v136, v112
	v_add_f32_e32 v153, v137, v113
	v_mfma_f32_32x32x16_bf16 v[16:31], v[100:103], v[132:135], v[16:31]
	v_add_f32_e64 v100, v108, v124
	v_add_f32_e64 v101, v109, v125
	v_add_f32_e64 v102, v142, v116
	v_add_f32_e64 v103, v143, v117
	v_exp_f32_e32 v134, v106
	v_exp_f32_e32 v135, v107
	v_exp_f32_e32 v132, v104
	v_exp_f32_e32 v133, v105
	v_add_f32_e32 v106, v138, v114
	v_add_f32_e32 v107, v139, v115
	v_mfma_f32_32x32x16_bf16 v[64:79], v[154:157], v[168:171], v[64:79]
	v_add_f32_e64 v154, v102, v100
	v_add_f32_e64 v155, v103, v101
	ds_read_b128 v[100:103], v141 offset:20480
	v_add_f32_e64 v104, v134, v122
	v_add_f32_e64 v105, v135, v123
	v_add_f32_e32 v150, v132, v120
	v_add_f32_e32 v151, v133, v121
	v_add_f32_e32 v104, v106, v104
	v_add_f32_e32 v105, v107, v105
	v_cvt_pk_bf16_f32 v184, v132, v133
	v_cvt_pk_bf16_f32 v185, v134, v135
	v_mfma_f32_32x32x16_bf16 v[64:79], v[146:149], v[172:175], v[64:79]
	v_add_f32_e64 v146, v110, v126
	v_add_f32_e64 v147, v111, v127
	v_add_f32_e64 v148, v144, v118
	v_add_f32_e64 v149, v145, v119
	s_waitcnt lgkmcnt(0)
	v_mfma_f32_32x32x16_bf16 v[0:15], v[96:99], v[128:131], v[0:15]
	v_add_f32_e64 v98, v148, v146
	v_add_f32_e64 v99, v149, v147
	v_add_f32_e64 v96, v152, v150
	v_add_f32_e64 v97, v153, v151
	v_add_f32_e64 v98, v104, v98
	v_add_f32_e64 v99, v105, v99
	ds_read_b128 v[104:107], v141 offset:24576
	v_add_f32_e32 v96, v96, v154
	v_add_f32_e32 v97, v97, v155
	s_nop 0
	v_add_f32_e32 v96, v96, v97
	v_mfma_f32_32x32x16_bf16 v[48:63], v[100:103], v[128:131], v[48:63]
	ds_read_b128 v[100:103], v141 offset:28672
	v_add_f32_e32 v97, v98, v99
	v_add_f32_e32 v146, v96, v97
	v_cvt_pk_bf16_f32 v96, v136, v137
	v_cvt_pk_bf16_f32 v97, v138, v139
	v_cvt_pk_bf16_f32 v98, v142, v143
	v_cvt_pk_bf16_f32 v99, v144, v145
	v_mfma_f32_32x32x16_bf16 v[80:95], v[176:179], v[168:171], v[80:95]
	v_cvt_pk_bf16_f32 v176, v120, v121
	v_cvt_pk_bf16_f32 v177, v122, v123
	v_cvt_pk_bf16_f32 v178, v124, v125
	v_cvt_pk_bf16_f32 v179, v126, v127
	s_waitcnt lgkmcnt(0)
	v_mfma_f32_32x32x16_bf16 v[32:47], v[104:107], v[128:131], v[32:47]
	v_mfma_f32_32x32x16_bf16 v[16:31], v[100:103], v[128:131], v[16:31]
	v_add_f32_e32 v100, v194, v146
	v_mfma_f32_32x32x16_bf16 v[80:95], v[238:241], v[172:175], v[80:95]
	s_cbranch_vccz .LBB0_842
	v_pk_mul_f32 v[14:15], v[140:141], v[14:15] op_sel_hi:[0,1]
	v_pk_mul_f32 v[12:13], v[140:141], v[12:13] op_sel_hi:[0,1]
	v_pk_mul_f32 v[10:11], v[140:141], v[10:11] op_sel_hi:[0,1]
	v_pk_mul_f32 v[8:9], v[140:141], v[8:9] op_sel_hi:[0,1]
	v_pk_mul_f32 v[6:7], v[140:141], v[6:7] op_sel_hi:[0,1]
	v_pk_mul_f32 v[4:5], v[140:141], v[4:5] op_sel_hi:[0,1]
	v_pk_mul_f32 v[2:3], v[140:141], v[2:3] op_sel_hi:[0,1]
	v_pk_mul_f32 v[0:1], v[140:141], v[0:1] op_sel_hi:[0,1]
	v_pk_mul_f32 v[62:63], v[140:141], v[62:63] op_sel_hi:[0,1]
	v_pk_mul_f32 v[60:61], v[140:141], v[60:61] op_sel_hi:[0,1]
	v_pk_mul_f32 v[58:59], v[140:141], v[58:59] op_sel_hi:[0,1]
	v_pk_mul_f32 v[56:57], v[140:141], v[56:57] op_sel_hi:[0,1]
	v_pk_mul_f32 v[54:55], v[140:141], v[54:55] op_sel_hi:[0,1]
	v_pk_mul_f32 v[52:53], v[140:141], v[52:53] op_sel_hi:[0,1]
	v_pk_mul_f32 v[50:51], v[140:141], v[50:51] op_sel_hi:[0,1]
	v_pk_mul_f32 v[48:49], v[140:141], v[48:49] op_sel_hi:[0,1]
	v_pk_mul_f32 v[46:47], v[140:141], v[46:47] op_sel_hi:[0,1]
	v_pk_mul_f32 v[44:45], v[140:141], v[44:45] op_sel_hi:[0,1]
	v_pk_mul_f32 v[42:43], v[140:141], v[42:43] op_sel_hi:[0,1]
	v_pk_mul_f32 v[40:41], v[140:141], v[40:41] op_sel_hi:[0,1]
	v_pk_mul_f32 v[38:39], v[140:141], v[38:39] op_sel_hi:[0,1]
	v_pk_mul_f32 v[36:37], v[140:141], v[36:37] op_sel_hi:[0,1]
	v_pk_mul_f32 v[34:35], v[140:141], v[34:35] op_sel_hi:[0,1]
	v_pk_mul_f32 v[32:33], v[140:141], v[32:33] op_sel_hi:[0,1]
	v_pk_mul_f32 v[30:31], v[140:141], v[30:31] op_sel_hi:[0,1]
	v_pk_mul_f32 v[28:29], v[140:141], v[28:29] op_sel_hi:[0,1]
	v_pk_mul_f32 v[26:27], v[140:141], v[26:27] op_sel_hi:[0,1]
	v_pk_mul_f32 v[24:25], v[140:141], v[24:25] op_sel_hi:[0,1]
	v_pk_mul_f32 v[22:23], v[140:141], v[22:23] op_sel_hi:[0,1]
	v_pk_mul_f32 v[20:21], v[140:141], v[20:21] op_sel_hi:[0,1]
	v_pk_mul_f32 v[18:19], v[140:141], v[18:19] op_sel_hi:[0,1]
	v_pk_mul_f32 v[16:17], v[140:141], v[16:17] op_sel_hi:[0,1]

.LBB0_862:
	s_andn2_b64 vcc, exec, s[0:1]
	s_cbranch_vccnz .LBB0_864
	s_add_i32 s0, s74, s64
	s_addk_i32 s0, 0xc0
	s_mul_i32 s0, s0, s14
	s_add_i32 s0, s0, s92
	s_addk_i32 s0, 0x1c00
	s_add_u32 s98, s82, s0
	s_addc_u32 s99, s83, 0
	s_lshl_b32 s1, s17, 13
	s_add_u32 s46, s76, s1
	s_addc_u32 s47, s77, 0
	s_add_i32 s0, s34, 0x8000
	s_and_b32 s0, s0, 0x18000
	s_add_i32 s0, s5, s0
	s_mov_b32 m0, s0
	s_nop 0
	global_load_lds_dwordx4 v244, s[98:99]
	s_add_i32 m0, s0, 0x2000
	s_add_u32 s98, s98, 0x80
	s_addc_u32 s99, s99, 0
	global_load_lds_dwordx4 v244, s[98:99]
	s_add_i32 m0, s0, 0x4000
	s_nop 0
	global_load_lds_dwordx4 v245, s[46:47]
	s_add_i32 m0, s0, 0x6000
	s_add_u32 s46, s46, 0x80000
	s_addc_u32 s47, s47, 0
	global_load_lds_dwordx4 v245, s[46:47]
	s_add_i32 s9, s34, 0x10000
	s_and_b32 s33, s9, 0x18000
	s_and_b32 s10, s34, 0x18000
	v_add_u32_e32 v250, s33, v237
	v_add_u32_e32 v250, v250, v230
	ds_read_b128 v[128:131], v250 offset:16384
	ds_read_b128 v[132:135], v250 offset:20480
	ds_read_b128 v[136:139], v250 offset:24576
	ds_read_b128 v[140:143], v250 offset:28672
	v_add_u32_e32 v251, s10, v236
	v_add_u32_e32 v250, v251, v230
	ds_read_b128 v[144:147], v250
	ds_read_b128 v[148:151], v250 offset:4096
	v_add_u32_e32 v250, v251, v233
	ds_read_b128 v[152:155], v250
	ds_read_b128 v[156:159], v250 offset:4096
	v_max3_f32 v246, v64, v65, v66
	v_max3_f32 v247, v72, v73, v74
	v_max3_f32 v248, v80, v81, v82
	v_max3_f32 v249, v88, v89, v90
	v_max3_f32 v246, v246, v67, v68
	v_max3_f32 v247, v247, v75, v76
	v_max3_f32 v248, v248, v83, v84
	v_max3_f32 v249, v249, v91, v92
	s_waitcnt lgkmcnt(7)
	v_mfma_f32_32x32x16_bf16 v[0:15], v[128:131], v[96:99], v[0:15]
	v_max3_f32 v246, v246, v69, v70
	v_max3_f32 v247, v247, v77, v78
	v_max3_f32 v248, v248, v85, v86
	v_max3_f32 v249, v249, v93, v94
	v_max3_f32 v246, v246, v71, v247
	v_max3_f32 v247, v248, v87, v249
	v_max_f32_e32 v248, v214, v214
	s_waitcnt lgkmcnt(6)
	v_mfma_f32_32x32x16_bf16 v[48:63], v[132:135], v[96:99], v[48:63]
	v_max3_f32 v246, v246, v79, v95
	s_nop 0
	v_max3_f32 v246, v246, v247, v247
	s_nop 0
	v_mov_b32_e32 v247, v246
	s_nop 1
	v_permlane32_swap_b32_e32 v246, v247
	v_max3_f32 v246, v246, v247, v247
	s_nop 0
	v_max_f32_e32 v247, v246, v246
	v_max_f32_e32 v251, v248, v247
	s_waitcnt lgkmcnt(5)
	v_mfma_f32_32x32x16_bf16 v[32:47], v[136:139], v[96:99], v[32:47]
	v_sub_f32_e32 v247, v214, v251
	v_exp_f32_e32 v250, v247
	v_add_f32_e32 v247, 0x41000000, v214
	v_cmp_gt_f32_e32 vcc, v246, v247
	s_cmp_eq_u64 vcc, 0
	v_mul_f32_e32 v246, v100, v250
	s_cselect_b64 s[0:1], -1, 0
	v_cndmask_b32_e64 v194, v246, v100, s[0:1]
	s_waitcnt lgkmcnt(4)
	v_mfma_f32_32x32x16_bf16 v[16:31], v[140:143], v[96:99], v[16:31]
	v_cndmask_b32_e64 v214, v251, v214, s[0:1]
	v_mov_b32_e32 v215, v214
	v_sub_f32_e32 v140, v92, v214
	v_sub_f32_e32 v141, v93, v215
	v_sub_f32_e32 v138, v90, v214
	v_sub_f32_e32 v139, v91, v215
	s_waitcnt lgkmcnt(3)
	v_mfma_f32_32x32x16_bf16 v[96:111], v[144:147], v[160:163], 0
	v_sub_f32_e32 v142, v94, v214
	v_sub_f32_e32 v143, v95, v215
	v_sub_f32_e32 v92, v80, v214
	v_sub_f32_e32 v93, v81, v215
	v_sub_f32_e32 v128, v82, v214
	v_sub_f32_e32 v129, v83, v215
	s_waitcnt lgkmcnt(2)
	v_mfma_f32_32x32x16_bf16 v[112:127], v[148:151], v[160:163], 0
	v_sub_f32_e32 v130, v68, v214
	v_sub_f32_e32 v131, v69, v215
	v_sub_f32_e32 v90, v64, v214
	v_sub_f32_e32 v91, v65, v215
	v_sub_f32_e32 v132, v84, v214
	v_sub_f32_e32 v133, v85, v215
	s_waitcnt lgkmcnt(1)
	v_mfma_f32_32x32x16_bf16 v[96:111], v[152:155], v[164:167], v[96:111]
	v_sub_f32_e32 v94, v66, v214
	v_sub_f32_e32 v95, v67, v215
	v_sub_f32_e32 v134, v86, v214
	v_sub_f32_e32 v135, v87, v215
	v_sub_f32_e32 v136, v88, v214
	v_sub_f32_e32 v137, v89, v215
	s_waitcnt lgkmcnt(0)
	v_mfma_f32_32x32x16_bf16 v[112:127], v[156:159], v[164:167], v[112:127]
	v_sub_f32_e32 v144, v70, v214
	v_sub_f32_e32 v145, v71, v215
	v_sub_f32_e32 v148, v74, v214
	v_sub_f32_e32 v149, v75, v215
	v_sub_f32_e32 v150, v76, v214
	v_sub_f32_e32 v151, v77, v215
	v_sub_f32_e32 v146, v72, v214
	v_sub_f32_e32 v147, v73, v215
	v_sub_f32_e32 v152, v78, v214
	v_sub_f32_e32 v153, v79, v215
	v_mov_b32_e32 v68, v250
	s_branch .Lattn_body_2
.LBB0_864:
	v_max3_f32 v64, v144, v145, v146
	v_max3_f32 v65, v152, v153, v154
	v_max3_f32 v66, v128, v129, v130
	v_max3_f32 v67, v136, v137, v138
	s_add_i32 s9, s34, 0x10000
	v_max3_f32 v64, v64, v147, v148
	v_max3_f32 v65, v65, v155, v156
	v_max3_f32 v66, v66, v131, v132
	v_max3_f32 v67, v67, v139, v140
	s_and_b32 s33, s9, 0x18000
	v_max3_f32 v64, v64, v149, v150
	v_max3_f32 v65, v65, v157, v158
	v_max3_f32 v66, v66, v133, v134
	v_max3_f32 v67, v67, v141, v142
	s_and_b32 s10, s34, 0x18000
	v_max3_f32 v64, v64, v151, v65
	v_max3_f32 v65, v66, v135, v67
	v_max_f32_e32 v66, v214, v214
	v_max3_f32 v64, v64, v159, v143
	s_nop 0
	v_max3_f32 v64, v64, v65, v65
	s_nop 0
	v_mov_b32_e32 v65, v64
	s_nop 1
	v_permlane32_swap_b32_e32 v64, v65
	v_max3_f32 v64, v64, v65, v65
	s_nop 0
	v_max_f32_e32 v65, v64, v64
	v_max_f32_e32 v69, v66, v65
	v_sub_f32_e32 v65, v214, v69
	v_exp_f32_e32 v68, v65
	v_add_f32_e32 v65, 0x41000000, v214
	v_cmp_gt_f32_e32 vcc, v64, v65
	s_cmp_eq_u64 vcc, 0
	v_mul_f32_e32 v64, v100, v68
	s_cselect_b64 s[0:1], -1, 0
	v_cndmask_b32_e64 v194, v64, v100, s[0:1]
	v_cndmask_b32_e64 v214, v69, v214, s[0:1]
	v_mov_b32_e32 v215, v214
	v_sub_f32_e32 v92, v128, v214
	v_sub_f32_e32 v93, v129, v215
	v_sub_f32_e32 v128, v130, v214
	v_sub_f32_e32 v129, v131, v215
	v_sub_f32_e32 v130, v148, v214
	v_sub_f32_e32 v131, v149, v215
	v_sub_f32_e32 v90, v144, v214
	v_sub_f32_e32 v91, v145, v215
	v_sub_f32_e32 v132, v132, v214
	v_sub_f32_e32 v133, v133, v215
	v_sub_f32_e32 v144, v150, v214
	v_sub_f32_e32 v145, v151, v215
	v_sub_f32_e32 v148, v154, v214
	v_sub_f32_e32 v149, v155, v215
	v_sub_f32_e32 v150, v156, v214
	v_sub_f32_e32 v151, v157, v215
	v_sub_f32_e32 v140, v140, v214
	v_sub_f32_e32 v141, v141, v215
	v_sub_f32_e32 v138, v138, v214
	v_sub_f32_e32 v139, v139, v215
	v_sub_f32_e32 v94, v146, v214
	v_sub_f32_e32 v95, v147, v215
	v_sub_f32_e32 v146, v152, v214
	v_sub_f32_e32 v147, v153, v215
	v_sub_f32_e32 v152, v158, v214
	v_sub_f32_e32 v153, v159, v215
	v_sub_f32_e32 v142, v142, v214
	v_sub_f32_e32 v143, v143, v215
	v_sub_f32_e32 v134, v134, v214
	v_sub_f32_e32 v135, v135, v215
	v_sub_f32_e32 v136, v136, v214
	v_sub_f32_e32 v137, v137, v215
	v_add_u32_e32 v74, s33, v237
	v_add_u32_e32 v74, v74, v230
	ds_read_b128 v[64:67], v74 offset:16384
	ds_read_b128 v[70:73], v74 offset:20480
	s_waitcnt lgkmcnt(0)
	v_mfma_f32_32x32x16_bf16 v[0:15], v[64:67], v[96:99], v[0:15]
	v_mfma_f32_32x32x16_bf16 v[48:63], v[70:73], v[96:99], v[48:63]
	ds_read_b128 v[64:67], v74 offset:24576
	ds_read_b128 v[70:73], v74 offset:28672
	s_waitcnt lgkmcnt(0)
	v_mfma_f32_32x32x16_bf16 v[32:47], v[64:67], v[96:99], v[32:47]
	v_mfma_f32_32x32x16_bf16 v[16:31], v[70:73], v[96:99], v[16:31]
	v_add_u32_e32 v74, s10, v236
	v_add_u32_e32 v74, v74, v230
	ds_read_b128 v[64:67], v74
	ds_read_b128 v[70:73], v74 offset:4096
	v_add_u32_e32 v74, s10, v236
	v_add_u32_e32 v74, v74, v233
	s_waitcnt lgkmcnt(0)
	v_mfma_f32_32x32x16_bf16 v[96:111], v[64:67], v[160:163], 0
	ds_read_b128 v[64:67], v74
	ds_read_b128 v[74:77], v74 offset:4096
	v_mfma_f32_32x32x16_bf16 v[112:127], v[70:73], v[160:163], 0
	s_waitcnt lgkmcnt(0)
	v_mfma_f32_32x32x16_bf16 v[96:111], v[64:67], v[164:167], v[96:111]
	v_mfma_f32_32x32x16_bf16 v[112:127], v[74:77], v[164:167], v[112:127]
.Lattn_body_2:
	v_add_u32_e32 v239, s33, v237
	v_add_u32_e32 v86, s10, v236
	v_add_u32_e32 v78, v239, v233
	v_add_u32_e32 v82, v86, v232
	v_add_u32_e32 v69, v239, v232
	v_exp_f32_e32 v130, v130
	v_exp_f32_e32 v154, v132
	v_exp_f32_e32 v131, v131
	v_exp_f32_e32 v155, v133
	v_add_u32_e32 v86, v86, v231
	v_exp_f32_e32 v158, v138
	v_exp_f32_e32 v159, v139
	v_exp_f32_e32 v94, v94
	v_exp_f32_e32 v128, v128
	v_exp_f32_e32 v95, v95
	v_exp_f32_e32 v129, v129
	v_exp_f32_e32 v132, v144
	v_exp_f32_e32 v144, v134
	v_exp_f32_e32 v133, v145
	v_exp_f32_e32 v145, v135
	v_exp_f32_e32 v148, v148
	v_exp_f32_e32 v149, v149
	v_exp_f32_e32 v142, v142
	v_exp_f32_e32 v143, v143
	ds_read_b128 v[64:67], v78 offset:16384
	ds_read_b128 v[70:73], v78 offset:20480
	v_exp_f32_e32 v90, v90
	v_exp_f32_e32 v92, v92
	v_exp_f32_e32 v91, v91
	v_exp_f32_e32 v93, v93
	v_exp_f32_e32 v146, v146
	v_exp_f32_e32 v156, v136
	v_exp_f32_e32 v147, v147
	v_exp_f32_e32 v157, v137
	v_add_f32_e32 v136, v90, v92
	v_add_f32_e32 v137, v91, v93
	s_waitcnt lgkmcnt(0)
	v_mfma_f32_32x32x16_bf16 v[0:15], v[64:67], v[184:187], v[0:15]
	ds_read_b128 v[64:67], v78 offset:24576
	ds_read_b128 v[74:77], v78 offset:28672
	ds_read_b128 v[78:81], v82
	ds_read_b128 v[82:85], v82 offset:4096
	v_mfma_f32_32x32x16_bf16 v[48:63], v[70:73], v[184:187], v[48:63]
	ds_read_b128 v[70:73], v86
	ds_read_b128 v[86:89], v86 offset:4096
	s_waitcnt lgkmcnt(0)
	v_mfma_f32_32x32x16_bf16 v[32:47], v[64:67], v[184:187], v[32:47]
	ds_read_b128 v[64:67], v69 offset:16384
	v_mfma_f32_32x32x16_bf16 v[16:31], v[74:77], v[184:187], v[16:31]
	ds_read_b128 v[74:77], v69 offset:20480
	s_waitcnt lgkmcnt(0)
	v_mfma_f32_32x32x16_bf16 v[0:15], v[64:67], v[180:183], v[0:15]
	ds_read_b128 v[64:67], v69 offset:24576
	v_mfma_f32_32x32x16_bf16 v[96:111], v[78:81], v[168:171], v[96:111]
	v_exp_f32_e32 v78, v150
	v_exp_f32_e32 v80, v140
	v_exp_f32_e32 v79, v151
	v_exp_f32_e32 v81, v141
	v_exp_f32_e32 v150, v152
	v_exp_f32_e32 v151, v153
	v_mfma_f32_32x32x16_bf16 v[48:63], v[74:77], v[180:183], v[48:63]
	ds_read_b128 v[74:77], v69 offset:28672
	v_add_u32_e32 v69, v239, v231
	v_add_f32_e64 v134, v150, v142
	v_add_f32_e64 v135, v151, v143
	s_waitcnt lgkmcnt(0)
	v_mfma_f32_32x32x16_bf16 v[32:47], v[64:67], v[180:183], v[32:47]
	ds_read_b128 v[64:67], v69 offset:16384
	v_mfma_f32_32x32x16_bf16 v[96:111], v[70:73], v[172:175], v[96:111]
	v_add_f32_e64 v70, v78, v80
	v_add_f32_e64 v71, v79, v81
	v_add_f32_e64 v72, v130, v154
	v_add_f32_e64 v73, v131, v155
	v_add_f32_e64 v138, v72, v70
	v_add_f32_e64 v139, v73, v71
	ds_read_b128 v[70:73], v69 offset:20480
	v_mfma_f32_32x32x16_bf16 v[16:31], v[74:77], v[180:183], v[16:31]
	v_add_f32_e64 v74, v148, v158
	v_add_f32_e64 v75, v149, v159
	v_add_f32_e64 v76, v94, v128
	v_add_f32_e64 v77, v95, v129
	v_add_f32_e64 v74, v76, v74
	v_add_f32_e64 v75, v77, v75
	v_mfma_f32_32x32x16_bf16 v[112:127], v[82:85], v[168:171], v[112:127]
	v_add_f32_e64 v82, v132, v144
	v_add_f32_e64 v83, v133, v145
	v_add_f32_e64 v84, v146, v156
	v_add_f32_e64 v85, v147, v157
	s_waitcnt lgkmcnt(0)
	v_mfma_f32_32x32x16_bf16 v[0:15], v[64:67], v[176:179], v[0:15]
	v_add_f32_e64 v66, v82, v134
	v_add_f32_e64 v67, v83, v135
	v_add_f32_e64 v64, v136, v84
	v_add_f32_e64 v65, v137, v85
	v_add_f32_e64 v66, v74, v66
	v_add_f32_e64 v67, v75, v67
	ds_read_b128 v[74:77], v69 offset:24576
	v_add_f32_e32 v64, v64, v138
	v_add_f32_e32 v65, v65, v139
	v_cvt_pk_bf16_f32 v134, v154, v155
	v_add_f32_e32 v64, v64, v65
	v_mfma_f32_32x32x16_bf16 v[48:63], v[70:73], v[176:179], v[48:63]
	ds_read_b128 v[70:73], v69 offset:28672
	v_add_f32_e32 v65, v66, v67
	v_add_f32_e32 v82, v64, v65
	v_cvt_pk_bf16_f32 v64, v90, v91
	v_cvt_pk_bf16_f32 v65, v94, v95
	v_cvt_pk_bf16_f32 v66, v130, v131
	v_cvt_pk_bf16_f32 v67, v132, v133
	s_waitcnt lgkmcnt(0)
	v_mfma_f32_32x32x16_bf16 v[32:47], v[74:77], v[176:179], v[32:47]
	v_cvt_pk_bf16_f32 v132, v92, v93
	v_cvt_pk_bf16_f32 v133, v128, v129
	v_cvt_pk_bf16_f32 v135, v144, v145
	v_cvt_pk_bf16_f32 v136, v146, v147
	v_cvt_pk_bf16_f32 v137, v148, v149
	v_cvt_pk_bf16_f32 v138, v78, v79
	v_cvt_pk_bf16_f32 v139, v150, v151
	v_mfma_f32_32x32x16_bf16 v[16:31], v[70:73], v[176:179], v[16:31]
	v_cvt_pk_bf16_f32 v128, v156, v157
	v_cvt_pk_bf16_f32 v129, v158, v159
	v_cvt_pk_bf16_f32 v130, v80, v81
	v_cvt_pk_bf16_f32 v131, v142, v143
	v_add_f32_e32 v69, v194, v82
	v_mfma_f32_32x32x16_bf16 v[112:127], v[86:89], v[172:175], v[112:127]
	s_cbranch_vccz .LBB0_866
	v_pk_mul_f32 v[14:15], v[68:69], v[14:15] op_sel_hi:[0,1]
	v_pk_mul_f32 v[12:13], v[68:69], v[12:13] op_sel_hi:[0,1]
	v_pk_mul_f32 v[10:11], v[68:69], v[10:11] op_sel_hi:[0,1]
	v_pk_mul_f32 v[8:9], v[68:69], v[8:9] op_sel_hi:[0,1]
	v_pk_mul_f32 v[6:7], v[68:69], v[6:7] op_sel_hi:[0,1]
	v_pk_mul_f32 v[4:5], v[68:69], v[4:5] op_sel_hi:[0,1]
	v_pk_mul_f32 v[2:3], v[68:69], v[2:3] op_sel_hi:[0,1]
	v_pk_mul_f32 v[0:1], v[68:69], v[0:1] op_sel_hi:[0,1]
	v_pk_mul_f32 v[62:63], v[68:69], v[62:63] op_sel_hi:[0,1]
	v_pk_mul_f32 v[60:61], v[68:69], v[60:61] op_sel_hi:[0,1]
	v_pk_mul_f32 v[58:59], v[68:69], v[58:59] op_sel_hi:[0,1]
	v_pk_mul_f32 v[56:57], v[68:69], v[56:57] op_sel_hi:[0,1]
	v_pk_mul_f32 v[54:55], v[68:69], v[54:55] op_sel_hi:[0,1]
	v_pk_mul_f32 v[52:53], v[68:69], v[52:53] op_sel_hi:[0,1]
	v_pk_mul_f32 v[50:51], v[68:69], v[50:51] op_sel_hi:[0,1]
	v_pk_mul_f32 v[48:49], v[68:69], v[48:49] op_sel_hi:[0,1]
	v_pk_mul_f32 v[46:47], v[68:69], v[46:47] op_sel_hi:[0,1]
	v_pk_mul_f32 v[44:45], v[68:69], v[44:45] op_sel_hi:[0,1]
	v_pk_mul_f32 v[42:43], v[68:69], v[42:43] op_sel_hi:[0,1]
	v_pk_mul_f32 v[40:41], v[68:69], v[40:41] op_sel_hi:[0,1]
	v_pk_mul_f32 v[38:39], v[68:69], v[38:39] op_sel_hi:[0,1]
	v_pk_mul_f32 v[36:37], v[68:69], v[36:37] op_sel_hi:[0,1]
	v_pk_mul_f32 v[34:35], v[68:69], v[34:35] op_sel_hi:[0,1]
	v_pk_mul_f32 v[32:33], v[68:69], v[32:33] op_sel_hi:[0,1]
	v_pk_mul_f32 v[30:31], v[68:69], v[30:31] op_sel_hi:[0,1]
	v_pk_mul_f32 v[28:29], v[68:69], v[28:29] op_sel_hi:[0,1]
	v_pk_mul_f32 v[26:27], v[68:69], v[26:27] op_sel_hi:[0,1]
	v_pk_mul_f32 v[24:25], v[68:69], v[24:25] op_sel_hi:[0,1]
	v_pk_mul_f32 v[22:23], v[68:69], v[22:23] op_sel_hi:[0,1]
	v_pk_mul_f32 v[20:21], v[68:69], v[20:21] op_sel_hi:[0,1]
	v_pk_mul_f32 v[18:19], v[68:69], v[18:19] op_sel_hi:[0,1]
	v_pk_mul_f32 v[16:17], v[68:69], v[16:17] op_sel_hi:[0,1]

.LBB0_870:
	s_add_i32 s0, s34, 0xffff8000
	s_and_b32 s33, s0, 0x18000
	v_add_u32_e32 v76, s33, v237
	v_add_u32_e32 v76, v76, v230
	ds_read_b128 v[80:83], v76 offset:16384
	ds_read_b128 v[84:87], v76 offset:20480
	ds_read_b128 v[88:91], v76 offset:24576
	ds_read_b128 v[92:95], v76 offset:28672
	v_max3_f32 v68, v96, v97, v98
	v_max3_f32 v70, v104, v105, v106
	v_max3_f32 v71, v112, v113, v114
	v_max3_f32 v72, v120, v121, v122
	v_max3_f32 v68, v68, v99, v100
	v_max3_f32 v70, v70, v107, v108
	v_max3_f32 v71, v71, v115, v116
	v_max3_f32 v72, v72, v123, v124
	s_waitcnt lgkmcnt(3)
	v_mfma_f32_32x32x16_bf16 v[0:15], v[80:83], v[64:67], v[0:15]
	v_max3_f32 v68, v68, v101, v102
	v_max3_f32 v70, v70, v109, v110
	v_max3_f32 v71, v71, v117, v118
	v_max3_f32 v72, v72, v125, v126
	s_xor_b32 s34, s33, 0x10000
	v_max3_f32 v68, v68, v103, v70
	v_max3_f32 v70, v71, v119, v72
	v_max_f32_e32 v71, v214, v214
	s_waitcnt lgkmcnt(2)
	v_mfma_f32_32x32x16_bf16 v[48:63], v[84:87], v[64:67], v[48:63]
	v_max3_f32 v68, v68, v111, v127
	s_nop 0
	v_max3_f32 v68, v68, v70, v70
	s_nop 0
	v_mov_b32_e32 v70, v68
	s_nop 1
	v_permlane32_swap_b32_e32 v68, v70
	v_max3_f32 v68, v68, v70, v70
	s_nop 0
	v_max_f32_e32 v70, v68, v68
	v_max_f32_e32 v141, v71, v70
	s_waitcnt lgkmcnt(1)
	v_mfma_f32_32x32x16_bf16 v[32:47], v[88:91], v[64:67], v[32:47]
	v_sub_f32_e32 v70, v214, v141
	v_exp_f32_e32 v140, v70
	v_add_f32_e32 v70, 0x41000000, v214
	v_cmp_gt_f32_e32 vcc, v68, v70
	s_cmp_eq_u64 vcc, 0
	v_mul_f32_e32 v68, v69, v140
	s_cselect_b64 s[0:1], -1, 0
	v_cndmask_b32_e64 v194, v68, v69, s[0:1]
	s_waitcnt lgkmcnt(0)
	v_mfma_f32_32x32x16_bf16 v[16:31], v[92:95], v[64:67], v[16:31]
	v_add_u32_e32 v182, s33, v237
	v_add_u32_e32 v158, s34, v236
	v_add_u32_e32 v88, v158, v233
	v_add_u32_e32 v150, v182, v233
	v_add_u32_e32 v159, v158, v232
	v_cndmask_b32_e64 v214, v141, v214, s[0:1]
	v_add_u32_e32 v141, v182, v232
	v_mov_b32_e32 v215, v214
	v_sub_f32_e32 v180, v102, v214
	v_sub_f32_e32 v181, v103, v215
	v_sub_f32_e32 v116, v116, v214
	v_sub_f32_e32 v117, v117, v215
	v_sub_f32_e32 v108, v108, v214
	v_sub_f32_e32 v109, v109, v215
	v_sub_f32_e32 v124, v124, v214
	v_sub_f32_e32 v125, v125, v215
	v_exp_f32_e32 v116, v116
	v_exp_f32_e32 v117, v117
	v_exp_f32_e32 v108, v108
	v_exp_f32_e32 v124, v124
	v_exp_f32_e32 v109, v109
	v_add_u32_e32 v68, v158, v230
	v_add_u32_e32 v158, v158, v231
	v_exp_f32_e32 v125, v125
	v_sub_f32_e32 v114, v114, v214
	v_sub_f32_e32 v115, v115, v215
	v_sub_f32_e32 v118, v118, v214
	v_sub_f32_e32 v119, v119, v215
	v_sub_f32_e32 v122, v122, v214
	v_sub_f32_e32 v123, v123, v215
	v_sub_f32_e32 v110, v110, v214
	v_sub_f32_e32 v111, v111, v215
	ds_read_b128 v[64:67], v68
	ds_read_b128 v[80:83], v68 offset:4096
	ds_read_b128 v[84:87], v88
	ds_read_b128 v[142:145], v88 offset:4096
	v_sub_f32_e32 v126, v126, v214
	v_sub_f32_e32 v127, v127, v215
	v_sub_f32_e32 v106, v106, v214
	v_sub_f32_e32 v107, v107, v215
	v_exp_f32_e32 v114, v114
	v_exp_f32_e32 v115, v115
	v_exp_f32_e32 v118, v118
	s_waitcnt lgkmcnt(0)
	v_mfma_f32_32x32x16_bf16 v[64:79], v[64:67], v[160:163], 0
	v_exp_f32_e32 v119, v119
	v_exp_f32_e32 v122, v122
	v_exp_f32_e32 v123, v123
	v_exp_f32_e32 v110, v110
	v_exp_f32_e32 v126, v126
	v_exp_f32_e32 v111, v111
	v_exp_f32_e32 v127, v127
	v_mfma_f32_32x32x16_bf16 v[64:79], v[84:87], v[164:167], v[64:79]
	v_sub_f32_e32 v104, v104, v214
	v_sub_f32_e32 v105, v105, v215
	v_sub_f32_e32 v112, v112, v214
	v_sub_f32_e32 v113, v113, v215
	v_sub_f32_e32 v120, v120, v214
	v_sub_f32_e32 v121, v121, v215
	v_cvt_pk_bf16_f32 v183, v118, v119
	v_exp_f32_e32 v112, v112
	v_exp_f32_e32 v113, v113
	v_exp_f32_e32 v120, v120
	v_mfma_f32_32x32x16_bf16 v[80:95], v[80:83], v[160:163], 0
	v_exp_f32_e32 v121, v121
	v_cvt_pk_bf16_f32 v186, v108, v109
	v_cvt_pk_bf16_f32 v187, v110, v111
	v_mfma_f32_32x32x16_bf16 v[80:95], v[142:145], v[164:167], v[80:95]
	ds_read_b128 v[142:145], v150 offset:16384
	ds_read_b128 v[146:149], v150 offset:20480
	s_waitcnt lgkmcnt(0)
	v_mfma_f32_32x32x16_bf16 v[0:15], v[142:145], v[136:139], v[0:15]
	ds_read_b128 v[142:145], v150 offset:24576
	ds_read_b128 v[150:153], v150 offset:28672
	ds_read_b128 v[154:157], v159
	ds_read_b128 v[176:179], v159 offset:4096
	v_mfma_f32_32x32x16_bf16 v[48:63], v[146:149], v[136:139], v[48:63]
	ds_read_b128 v[146:149], v158
	ds_read_b128 v[238:241], v158 offset:4096
	v_sub_f32_e32 v158, v96, v214
	v_sub_f32_e32 v159, v97, v215
	s_waitcnt lgkmcnt(0)
	v_mfma_f32_32x32x16_bf16 v[32:47], v[142:145], v[136:139], v[32:47]
	v_sub_f32_e32 v142, v98, v214
	v_sub_f32_e32 v143, v99, v215
	v_sub_f32_e32 v144, v100, v214
	v_sub_f32_e32 v145, v101, v215
	ds_read_b128 v[96:99], v141 offset:16384
	ds_read_b128 v[100:103], v141 offset:20480
	s_waitcnt lgkmcnt(0)
	v_mfma_f32_32x32x16_bf16 v[0:15], v[96:99], v[132:135], v[0:15]
	ds_read_b128 v[96:99], v141 offset:24576
	v_mfma_f32_32x32x16_bf16 v[48:63], v[100:103], v[132:135], v[48:63]
	ds_read_b128 v[100:103], v141 offset:28672
	v_add_u32_e32 v141, v182, v231
	v_cvt_pk_bf16_f32 v182, v116, v117
	v_mfma_f32_32x32x16_bf16 v[16:31], v[150:153], v[136:139], v[16:31]
	v_exp_f32_e32 v138, v142
	v_exp_f32_e32 v139, v143
	v_exp_f32_e32 v142, v144
	v_exp_f32_e32 v143, v145
	v_exp_f32_e32 v144, v180
	v_exp_f32_e32 v145, v181
	v_exp_f32_e32 v136, v158
	s_waitcnt lgkmcnt(0)
	v_mfma_f32_32x32x16_bf16 v[32:47], v[96:99], v[132:135], v[32:47]
	ds_read_b128 v[96:99], v141 offset:16384
	v_exp_f32_e32 v137, v159
	v_cvt_pk_bf16_f32 v180, v112, v113
	v_cvt_pk_bf16_f32 v181, v114, v115
	v_add_f32_e32 v152, v136, v112
	v_add_f32_e32 v153, v137, v113
	v_mfma_f32_32x32x16_bf16 v[16:31], v[100:103], v[132:135], v[16:31]
	v_add_f32_e64 v100, v108, v124
	v_add_f32_e64 v101, v109, v125
	v_add_f32_e64 v102, v142, v116
	v_add_f32_e64 v103, v143, v117
	v_exp_f32_e32 v134, v106
	v_exp_f32_e32 v135, v107
	v_exp_f32_e32 v132, v104
	v_exp_f32_e32 v133, v105
	v_add_f32_e32 v106, v138, v114
	v_add_f32_e32 v107, v139, v115
	v_mfma_f32_32x32x16_bf16 v[64:79], v[154:157], v[168:171], v[64:79]
	v_add_f32_e64 v154, v102, v100
	v_add_f32_e64 v155, v103, v101
	ds_read_b128 v[100:103], v141 offset:20480
	v_add_f32_e64 v104, v134, v122
	v_add_f32_e64 v105, v135, v123
	v_add_f32_e32 v150, v132, v120
	v_add_f32_e32 v151, v133, v121
	v_add_f32_e32 v104, v106, v104
	v_add_f32_e32 v105, v107, v105
	v_cvt_pk_bf16_f32 v184, v132, v133
	v_cvt_pk_bf16_f32 v185, v134, v135
	v_mfma_f32_32x32x16_bf16 v[64:79], v[146:149], v[172:175], v[64:79]
	v_add_f32_e64 v146, v110, v126
	v_add_f32_e64 v147, v111, v127
	v_add_f32_e64 v148, v144, v118
	v_add_f32_e64 v149, v145, v119
	s_waitcnt lgkmcnt(0)
	v_mfma_f32_32x32x16_bf16 v[0:15], v[96:99], v[128:131], v[0:15]
	v_add_f32_e64 v98, v148, v146
	v_add_f32_e64 v99, v149, v147
	v_add_f32_e64 v96, v152, v150
	v_add_f32_e64 v97, v153, v151
	v_add_f32_e64 v98, v104, v98
	v_add_f32_e64 v99, v105, v99
	ds_read_b128 v[104:107], v141 offset:24576
	v_add_f32_e32 v96, v96, v154
	v_add_f32_e32 v97, v97, v155
	s_nop 0
	v_add_f32_e32 v96, v96, v97
	v_mfma_f32_32x32x16_bf16 v[48:63], v[100:103], v[128:131], v[48:63]
	ds_read_b128 v[100:103], v141 offset:28672
	v_add_f32_e32 v97, v98, v99
	v_add_f32_e32 v146, v96, v97
	v_cvt_pk_bf16_f32 v96, v136, v137
	v_cvt_pk_bf16_f32 v97, v138, v139
	v_cvt_pk_bf16_f32 v98, v142, v143
	v_cvt_pk_bf16_f32 v99, v144, v145
	v_mfma_f32_32x32x16_bf16 v[80:95], v[176:179], v[168:171], v[80:95]
	v_cvt_pk_bf16_f32 v176, v120, v121
	v_cvt_pk_bf16_f32 v177, v122, v123
	v_cvt_pk_bf16_f32 v178, v124, v125
	v_cvt_pk_bf16_f32 v179, v126, v127
	s_waitcnt lgkmcnt(0)
	v_mfma_f32_32x32x16_bf16 v[32:47], v[104:107], v[128:131], v[32:47]
	v_mfma_f32_32x32x16_bf16 v[16:31], v[100:103], v[128:131], v[16:31]
	v_add_f32_e32 v100, v194, v146
	v_mfma_f32_32x32x16_bf16 v[80:95], v[238:241], v[172:175], v[80:95]
	s_cbranch_vccz .LBB0_872
	v_pk_mul_f32 v[14:15], v[140:141], v[14:15] op_sel_hi:[0,1]
	v_pk_mul_f32 v[12:13], v[140:141], v[12:13] op_sel_hi:[0,1]
	v_pk_mul_f32 v[10:11], v[140:141], v[10:11] op_sel_hi:[0,1]
	v_pk_mul_f32 v[8:9], v[140:141], v[8:9] op_sel_hi:[0,1]
	v_pk_mul_f32 v[6:7], v[140:141], v[6:7] op_sel_hi:[0,1]
	v_pk_mul_f32 v[4:5], v[140:141], v[4:5] op_sel_hi:[0,1]
	v_pk_mul_f32 v[2:3], v[140:141], v[2:3] op_sel_hi:[0,1]
	v_pk_mul_f32 v[0:1], v[140:141], v[0:1] op_sel_hi:[0,1]
	v_pk_mul_f32 v[62:63], v[140:141], v[62:63] op_sel_hi:[0,1]
	v_pk_mul_f32 v[60:61], v[140:141], v[60:61] op_sel_hi:[0,1]
	v_pk_mul_f32 v[58:59], v[140:141], v[58:59] op_sel_hi:[0,1]
	v_pk_mul_f32 v[56:57], v[140:141], v[56:57] op_sel_hi:[0,1]
	v_pk_mul_f32 v[54:55], v[140:141], v[54:55] op_sel_hi:[0,1]
	v_pk_mul_f32 v[52:53], v[140:141], v[52:53] op_sel_hi:[0,1]
	v_pk_mul_f32 v[50:51], v[140:141], v[50:51] op_sel_hi:[0,1]
	v_pk_mul_f32 v[48:49], v[140:141], v[48:49] op_sel_hi:[0,1]
	v_pk_mul_f32 v[46:47], v[140:141], v[46:47] op_sel_hi:[0,1]
	v_pk_mul_f32 v[44:45], v[140:141], v[44:45] op_sel_hi:[0,1]
	v_pk_mul_f32 v[42:43], v[140:141], v[42:43] op_sel_hi:[0,1]
	v_pk_mul_f32 v[40:41], v[140:141], v[40:41] op_sel_hi:[0,1]
	v_pk_mul_f32 v[38:39], v[140:141], v[38:39] op_sel_hi:[0,1]
	v_pk_mul_f32 v[36:37], v[140:141], v[36:37] op_sel_hi:[0,1]
	v_pk_mul_f32 v[34:35], v[140:141], v[34:35] op_sel_hi:[0,1]
	v_pk_mul_f32 v[32:33], v[140:141], v[32:33] op_sel_hi:[0,1]
	v_pk_mul_f32 v[30:31], v[140:141], v[30:31] op_sel_hi:[0,1]
	v_pk_mul_f32 v[28:29], v[140:141], v[28:29] op_sel_hi:[0,1]
	v_pk_mul_f32 v[26:27], v[140:141], v[26:27] op_sel_hi:[0,1]
	v_pk_mul_f32 v[24:25], v[140:141], v[24:25] op_sel_hi:[0,1]
	v_pk_mul_f32 v[22:23], v[140:141], v[22:23] op_sel_hi:[0,1]
	v_pk_mul_f32 v[20:21], v[140:141], v[20:21] op_sel_hi:[0,1]
	v_pk_mul_f32 v[18:19], v[140:141], v[18:19] op_sel_hi:[0,1]
	v_pk_mul_f32 v[16:17], v[140:141], v[16:17] op_sel_hi:[0,1]
